# P1: main-GEMM prologue issues K-tile 1's six LDS-DMA pieces before the first wait (vmcnt 2 -> 8), overlapping the two cold round trips
# baseline (speedup 1.0000x reference)
; #define PG8_STAGE(bufoff, gbase, voff) do { _Pragma("unroll") for (int _i = 0; _i < 2; ++_i) \
;         __builtin_amdgcn_global_load_lds((const unsigned*)((const char*)(gbase) + (voff)[_i]), (PG8_LAS unsigned*)(lds + (bufoff) + ldsw + _i * 8192), 16, 0, 0); } while (0)
; #define PG8_WAIT_V(n) asm volatile("s_waitcnt vmcnt(" #n ")" ::: "memory")
; #define PG8_BAR __builtin_amdgcn_s_barrier()
; template <class Epi, class Sched, bool ALIGN_EPI = false, bool SP2 = false>
; __device__ __forceinline__ void gemm_phase(PG8_LAS unsigned char* lds, const Gemm g, const Sched& S, const Epi& E) {
;     ...
;     const int tid = tid_l, wid = __builtin_amdgcn_readfirstlane(tid >> 6), lane = tid & 63, wr = wid >> 2, wc = wid & 3, fr = lane & 15, fq = lane >> 4;
;     const int K = g.K, nt = K / BK;
;     unsigned voffA[2], voffB[2];
; #pragma unroll
;     for (int i = 0; i < 2; ++i) { int R, C; stage_rc(tid * 16 + i * 8192, R, C); const int Rb = Epi::PERM ? ((R & ~31) + perm32(R & 31)) : R;
;         voffA[i] = (unsigned)(R * K + C) * 2u; voffB[i] = (unsigned)(Rb * K + C) * 2u; }
;     const size_t kstep = (size_t)(BK * 2);
;     const size_t hstep = (size_t)HALF * K * 2;
;     const size_t tstep = 2 * hstep;
;     const unsigned ldsw = (unsigned)wid * 1024u;
;     const int aoff = lds_byte(wr * 64 + fr, fq * 8), boff = lds_byte(wc * 32 + fr, fq * 8);
;     ...
;     if constexpr (SP2) {
;         PG8_STAGE(PG8_SB(0, 0), cB, voffB); PG8_STAGE(PG8_SB(0, 1), cB + hstep, voffB); PG8_STAGE(PG8_SA(0, 0), cA, voffA); PG8_STAGE(PG8_SA(0, 1), cA + hstep, voffA);
;         if (wr == 1) PG8_BAR;
;         PG8_WAIT_V(2); PG8_BAR;
;         PG8_STAGE(PG8_SB(1, 0), cB + kstep, voffB); PG8_STAGE(PG8_SA(1, 0), cA + kstep, voffA); PG8_STAGE(PG8_SB(1, 1), cB + hstep + kstep, voffB);
;         PG8_WAIT_V(6); PG8_BAR;
.LBB0_404:
	s_add_i32 m0, s61, 0x18000
	v_lshl_add_u64 v[10:11], v[10:11], 0, s[24:25]
	global_load_lds_dwordx4 v[10:11], off
	v_lshl_add_u64 v[6:7], v[6:7], 0, s[24:25]
	s_add_i32 m0, s61, 0x1a000
	s_add_i32 s80, s61, 0x8000
	global_load_lds_dwordx4 v[6:7], off
	v_lshl_add_u64 v[6:7], v[8:9], 0, s[24:25]
	s_mov_b32 m0, s80
	s_add_i32 s81, s61, 0xa000
	global_load_lds_dwordx4 v[6:7], off
	v_lshl_add_u64 v[6:7], v[12:13], 0, s[24:25]
	s_mov_b32 m0, s81
	v_lshl_add_u64 v[4:5], v[4:5], 0, s[24:25]
	global_load_lds_dwordx4 v[6:7], off
	s_add_i32 m0, s61, 0x1c000
	v_lshl_add_u64 v[2:3], v[2:3], 0, s[24:25]
	global_load_lds_dwordx4 v[4:5], off
	s_add_i32 m0, s61, 0x1e000
	s_lshl_b32 s19, s19, 5
	global_load_lds_dwordx4 v[2:3], off
	s_waitcnt vmcnt(8)
	s_barrier
	v_lshrrev_b32_e32 v3, 1, v14
	v_and_b32_e32 v3, 24, v3
	v_and_b32_e32 v2, 15, v14
	v_lshlrev_b32_e32 v4, 1, v3
	v_lshl_or_b32 v160, s31, 6, v2
	v_lshl_or_b32 v2, v2, 6, v4
	v_lshlrev_b32_e32 v4, 2, v14
	s_lshl_b32 s31, s31, 13
	v_and_b32_e32 v4, 32, v4
	v_bitop3_b32 v5, v2, s31, v4 bitop3:0xde
	s_and_b32 s31, s19, 0x60
	s_lshl_b32 s19, s31, 7
	v_bitop3_b32 v161, v2, s19, v4 bitop3:0xde
	v_cvt_f32_ubyte0_e32 v2, s54
	v_rcp_iflag_f32_e32 v2, v2
	s_lshr_b32 s82, s82, 6
	s_add_i32 s83, s82, -2
	s_cmpk_lt_u32 s30, 0x100
	v_mul_f32_e32 v2, 0x4f7ffffe, v2
	v_cvt_u32_f32_e32 v2, v2
	s_cselect_b64 s[34:35], -1, 0
	v_or_b32_e32 v162, s31, v3
	s_sub_i32 s30, 0, s54
	v_readfirstlane_b32 s31, v2
	s_waitcnt vmcnt(6)
	s_mul_i32 s30, s30, s31
	s_mul_hi_u32 s30, s31, s30
	s_mov_b32 s19, s11
	s_mov_b32 s84, 0
	s_add_i32 s85, s31, s30
	v_lshl_add_u64 v[152:153], s[10:11], 0, v[146:147]
	v_lshl_add_u64 v[154:155], s[10:11], 0, v[148:149]
	v_add_u32_e32 v163, 0, v5
	s_barrier
	s_branch .LBB0_407
